# cv21 + the idle workgroups of the layer-0 in-projection tail also convert 3200 layer-0 blocks (w_out_a/b, w_o, start of w_gate_up), P2(0) starts after them
# speedup vs baseline: 1.0136x; 1.0056x over previous
.Lcv_entry:
	s_waitcnt vmcnt(0) lgkmcnt(0)
	v_writelane_b32 v254, s4, 0
	v_writelane_b32 v254, s5, 1
	v_writelane_b32 v254, s6, 2
	v_writelane_b32 v254, s7, 3
	v_writelane_b32 v254, s8, 4
	v_writelane_b32 v254, s9, 5
	v_writelane_b32 v254, s10, 6
	v_writelane_b32 v254, s11, 7
	v_writelane_b32 v254, s12, 8
	v_writelane_b32 v254, s13, 9
	v_writelane_b32 v254, s14, 10
	v_writelane_b32 v254, s15, 11
	v_writelane_b32 v254, s16, 12
	v_writelane_b32 v254, s17, 13
	v_writelane_b32 v254, s18, 14
	v_writelane_b32 v254, s19, 15
	v_writelane_b32 v254, s20, 16
	v_writelane_b32 v254, s21, 17
	v_writelane_b32 v254, s22, 18
	v_writelane_b32 v254, s23, 19
	v_writelane_b32 v254, s24, 20
	v_writelane_b32 v254, s25, 21
	v_writelane_b32 v254, s26, 22
	v_writelane_b32 v254, s27, 23
	v_writelane_b32 v254, s28, 24
	v_writelane_b32 v254, s29, 25
	v_writelane_b32 v254, s30, 26
	v_writelane_b32 v254, s31, 27
	v_writelane_b32 v254, s32, 28
	v_writelane_b32 v254, s33, 29
	v_writelane_b32 v254, s34, 30
	v_writelane_b32 v254, s35, 31
	v_writelane_b32 v254, s36, 32
	v_writelane_b32 v254, s37, 33
	v_writelane_b32 v254, s38, 34
	v_writelane_b32 v254, s39, 35
	v_writelane_b32 v254, s40, 36
	v_writelane_b32 v254, s41, 37
	v_writelane_b32 v254, s42, 38
	v_writelane_b32 v254, s43, 39
	v_writelane_b32 v254, s44, 40
	v_writelane_b32 v254, s45, 41
	v_writelane_b32 v254, s46, 42
	v_writelane_b32 v254, s47, 43
	v_writelane_b32 v254, s48, 44
	v_writelane_b32 v254, s49, 45
	v_writelane_b32 v254, s50, 46
	v_writelane_b32 v254, s51, 47
	v_writelane_b32 v254, s52, 48
	v_writelane_b32 v254, s53, 49
	s_mov_b32 s52, 0
	v_readlane_b32 s4, v253, 0
	v_readlane_b32 s5, v253, 1
	s_sub_u32 s4, s4, 0xd0
	s_subb_u32 s5, s5, 0
	s_load_dwordx2 s[6:7], s[4:5], 0xc0
	v_readfirstlane_b32 s29, v0
	s_lshr_b32 s29, s29, 6
	v_and_b32_e32 v8, 63, v0
	v_lshrrev_b32_e32 v9, 4, v8
	v_and_b32_e32 v10, 15, v8
	v_and_b32_e32 v11, 7, v8
	v_lshrrev_b32_e32 v13, 3, v8
	v_lshlrev_b32_e32 v4, 3, v9
	s_mul_i32 s31, s29, 0x2100
	v_mul_u32_u24_e32 v5, 0x108, v9
	v_lshlrev_b32_e32 v14, 4, v10
	v_add3_u32 v5, v5, v14, s31
	v_mul_u32_u24_e32 v6, 0x420, v11
	v_lshlrev_b32_e32 v15, 2, v13
	v_add3_u32 v6, v6, v15, s31
	v_lshlrev_b32_e32 v9, 1, v9
	v_lshlrev_b32_e32 v11, 4, v11
	s_and_b32 s31, s3, 7
	s_cmp_eq_u32 s31, 0
	s_cbranch_scc0 .Lcv_vcu_plain
	s_and_b32 s31, s2, 7
	s_lshr_b32 s32, s3, 3
	s_mul_i32 s31, s31, s32
	s_lshr_b32 s32, s2, 3
	s_add_u32 s31, s31, s32
	s_branch .Lcv_vcu_done

.Lcv_site_p2:
	s_cmp_gt_u32 s98, 2
	s_cbranch_scc1 .Lcv_site_tail
	s_add_u32 s9, s30, 2
	s_mul_i32 s9, s9, 0x4180
	s_sub_u32 s8, s9, 0x4180
	s_cmp_eq_u32 s30, 0
	s_cselect_b32 s8, 0x1680, s8
	s_add_u32 s8, s8, s31
	s_mov_b32 s10, s66
	s_cmp_eq_u32 s3, 0x100
	s_cselect_b32 s32, 6400, 0
	s_cselect_b32 s47, 3200, 0
	s_sub_u32 s9, s9, s32
	s_cmp_eq_u32 s30, 0
	s_cselect_b32 s47, s47, 0
	s_add_u32 s8, s8, s47
	s_branch .Lcv_go
.Lcv_site_tail:
	s_cmp_eq_u32 s3, 0x100
	s_cbranch_scc0 .Lcv_exit0
	s_cmp_lt_u32 s2, 216
	s_cbranch_scc1 .Lcv_exit0
	s_cmp_eq_u32 s98, 3
	s_cbranch_scc0 .Lcv_site_t5
	s_cmp_eq_u32 s30, 0
	s_cbranch_scc0 .Lcv_site_t3n
	s_mov_b32 s9, 8960
	s_branch .Lcv_site_tc
.Lcv_site_t3n:
	s_add_u32 s9, s30, 1
	s_mul_i32 s9, s9, 0x4180
	s_sub_u32 s9, s9, 3200
	s_branch .Lcv_site_tc

.Lcv_go2:
	s_cmp_ge_u32 s8, s9
	s_cbranch_scc1 .Lcv_exit
	s_mov_b32 s11, s8
	s_mov_b32 s12, 0
	s_mov_b32 s13, s11
	s_cmp_ge_u32 s13, 0x4180
	s_cbranch_scc0 .Lcv_d0_l
	s_sub_u32 s13, s13, 0x4180
	s_add_u32 s12, s12, 1
	s_cmp_ge_u32 s13, 0x4180
	s_cbranch_scc0 .Lcv_d0_l
	s_sub_u32 s13, s13, 0x4180
	s_add_u32 s12, s12, 1
	s_cmp_ge_u32 s13, 0x4180
	s_cbranch_scc0 .Lcv_d0_l
	s_sub_u32 s13, s13, 0x4180
	s_add_u32 s12, s12, 1
